# prep: the per-direction mLSTM gate-bias loads are fetched once per phase instead of inside every job, removing two full VMEM drains per job from wave 0
# speedup vs baseline: 1.0118x; 1.0041x over previous
.LBB0_617:
	s_mov_b32 s101, 0
	v_writelane_b32 v255, s56, 8
	s_movk_i32 s8, 0xd0
	s_movk_i32 s2, 0x80
	v_writelane_b32 v255, s57, 9
	v_writelane_b32 v255, s82, 16
	s_mov_b32 s31, s57
	s_and_b64 vcc, exec, s[40:41]
	v_writelane_b32 v255, s83, 17
	v_writelane_b32 v255, s84, 10
	v_readlane_b32 s3, v254, 0
	s_nop 0
	v_writelane_b32 v255, s85, 11
	v_writelane_b32 v255, s86, 12
	v_writelane_b32 v255, s87, 13
	s_cbranch_vccnz .LBB0_663
	v_lshrrev_b16_e32 v126, 11, v126
	v_readlane_b32 s10, v255, 3
	v_mul_lo_u16_e32 v0, 12, v126
	v_readlane_b32 s11, v255, 4
	v_sub_u16_e32 v0, v158, v0
	s_load_dwordx4 s[84:87], s[10:11], 0x158
	s_load_dwordx4 s[88:91], s[10:11], 0xa0
	v_lshlrev_b16_e32 v0, 3, v0
	s_movk_i32 s3, 0x1556
	v_and_b32_e32 v100, 0xf8, v0
	v_mul_u32_u24_sdwa v0, v129, s3 dst_sel:DWORD dst_unused:UNUSED_PAD src0_sel:WORD_0 src1_sel:DWORD
	v_lshrrev_b32_e32 v128, 16, v0
	v_mul_lo_u16_e32 v0, 12, v128
	v_sub_u16_e32 v0, v129, v0
	v_lshlrev_b16_e32 v102, 3, v0
	v_mul_u32_u24_sdwa v0, v130, s3 dst_sel:DWORD dst_unused:UNUSED_PAD src0_sel:WORD_0 src1_sel:DWORD
	s_waitcnt lgkmcnt(0)
	s_add_u32 s10, s84, 0x37fa400
	v_lshrrev_b32_e32 v129, 16, v0
	s_addc_u32 s11, s85, 0
	v_mul_lo_u16_e32 v0, 12, v129
	v_writelane_b32 v255, s10, 14
	v_sub_u16_e32 v0, v130, v0
	v_lshlrev_b16_e32 v104, 3, v0
	v_writelane_b32 v255, s11, 15
	v_and_b32_e32 v0, 63, v158
	s_add_u32 s12, s84, 0x3246000
	v_readlane_b32 s10, v255, 5
	s_addc_u32 s13, s85, 0
	s_lshl_b32 s3, s10, 3
	v_cmp_eq_u32_e64 s[44:45], 0, v0
	v_cmp_gt_u32_e64 s[46:47], 2, v0
	v_cmp_gt_u32_e64 s[48:49], 4, v0
	v_cmp_gt_u32_e64 s[50:51], 8, v0
	v_cmp_gt_u32_e64 s[52:53], 16, v0
	v_cmp_gt_u32_e64 s[54:55], 32, v0
	v_lshl_add_u32 v134, v0, 2, v124
	v_subrev_co_u32_e32 v0, vcc, s2, v123
	s_movk_i32 s2, 0x60
	s_waitcnt vmcnt(10)
	v_and_b32_e32 v40, 15, v158
	v_readlane_b32 s11, v255, 6
	v_writelane_b32 v255, s3, 7
	v_cmp_gt_u32_e64 s[56:57], s2, v0
	s_waitcnt vmcnt(4)
	v_lshl_add_u64 v[2:3], v[0:1], 2, s[84:85]
	s_mov_b64 s[2:3], 0x366e400
	v_and_b32_e32 v0, 48, v158
	v_lshl_add_u64 v[106:107], v[2:3], 0, s[2:3]
	v_add_u32_e32 v2, v124, v0
	v_mul_u32_u24_e32 v0, 0x68, v40
	v_lshl_add_u32 v137, v0, 1, v2
	v_lshrrev_b32_e32 v0, 2, v158
	v_and_b32_e32 v0, 12, v0
	v_cmp_eq_u32_e64 s[58:59], 3, v127
	v_cmp_ne_u32_e64 s[68:69], 3, v127
	v_or_b32_e32 v127, v0, v125
	v_lshlrev_b32_e32 v41, 1, v40
	v_mul_u32_u24_e32 v3, 0x48, v127
	v_add_u32_e32 v42, v124, v41
	v_lshlrev_b32_e32 v3, 1, v3
	v_add_u32_e32 v143, v42, v3
	v_add_u32_e32 v43, 0x90, v3
	v_add_u32_e32 v44, 0x120, v3
	v_add_u32_e32 v3, 0x1b0, v3
	v_add_u32_e32 v144, v42, v43
	v_add_u32_e32 v145, v42, v44
	v_add_u32_e32 v146, v42, v3
	v_or_b32_e32 v42, 16, v40
	v_cmp_gt_u32_e64 s[42:43], 64, v123
	s_add_u32 s22, s84, 0x3666000
	v_or_b32_e32 v139, 1, v127
	v_cmp_gt_u32_e64 s[70:71], v42, v127
	s_addc_u32 s23, s85, 0
	v_or_b32_e32 v140, 2, v127
	s_or_b64 s[26:27], s[42:43], s[70:71]
	v_cmp_gt_u32_e64 s[70:71], v42, v139
	v_or_b32_e32 v141, 3, v127
	s_or_b64 s[28:29], s[42:43], s[70:71]
	v_cmp_gt_u32_e64 s[70:71], v42, v140
	s_or_b64 s[78:79], s[42:43], s[70:71]
	v_cmp_gt_u32_e64 s[70:71], v42, v141
	v_add3_u32 v159, v124, v3, v41
	v_or_b32_e32 v3, 32, v40
	s_or_b64 s[84:85], s[42:43], s[70:71]
	v_cmp_gt_u32_e64 s[70:71], v3, v127
	s_or_b64 s[92:93], vcc, s[70:71]
	v_cmp_gt_u32_e64 s[70:71], v3, v139
	s_or_b64 s[72:73], vcc, s[70:71]
	v_cmp_gt_u32_e64 s[70:71], v3, v140
	s_or_b64 s[14:15], vcc, s[70:71]
	v_cmp_gt_u32_e64 s[70:71], v3, v141
	v_or_b32_e32 v3, 48, v40
	s_xor_b64 s[24:25], vcc, -1
	v_or_b32_e32 v135, v125, v40
	s_or_b64 s[34:35], vcc, s[70:71]
	v_cmp_gt_u32_e32 vcc, v3, v127
	v_mad_u32_u24 v136, v135, s8, v2
	s_or_b64 s[8:9], s[68:69], vcc
	v_cmp_gt_u32_e32 vcc, v3, v139
	s_or_b64 s[10:11], s[68:69], vcc
	v_cmp_gt_u32_e32 vcc, v3, v140
	s_movk_i32 s2, 0x90
	s_or_b64 s[18:19], s[68:69], vcc
	v_cmp_gt_u32_e32 vcc, v3, v141
	v_mad_u32_u24 v164, v135, s2, v2
	v_bfe_u32 v2, v158, 2, 2
	v_lshrrev_b32_e32 v3, 1, v158
	v_lshl_add_u32 v138, v127, 2, v124
	v_mul_u32_u24_e32 v45, 0x8c, v127
	v_and_or_b32 v2, v3, 24, v2
	v_readlane_b32 s2, v254, 58
	v_lshl_add_u32 v142, v40, 2, v124
	v_cmp_gt_u32_e64 s[60:61], v40, v127
	v_cmp_gt_u32_e64 s[62:63], v40, v139
	v_cmp_gt_u32_e64 s[64:65], v40, v140
	v_cmp_gt_u32_e64 s[66:67], v40, v141
	v_add3_u32 v147, v138, v45, v41
	v_add3_u32 v148, v124, v43, v41
	v_add3_u32 v149, v124, v44, v41
	s_or_b64 s[94:95], s[68:69], vcc
	v_cmp_eq_u32_e64 s[68:69], 0, v40
	v_bitop3_b32 v160, v0, 63, v125 bitop3:0x36
	v_bitop3_b32 v161, v0, 62, v125 bitop3:0x36
	v_bitop3_b32 v162, v0, 61, v125 bitop3:0x36
	v_bitop3_b32 v163, v0, 60, v125 bitop3:0x36
	v_bitop3_b32 v125, v125, 63, v40 bitop3:0x36
	v_mul_u32_u24_e32 v2, 0xd0, v2
	v_add_u32_e32 v166, s2, v93
	v_readlane_b32 s2, v254, 59
	v_mov_b64_e32 v[42:43], v[6:7]
	v_mov_b64_e32 v[50:51], v[14:15]
	s_waitcnt vmcnt(0)
	v_mov_b64_e32 v[66:67], v[26:27]
	v_mov_b64_e32 v[46:47], v[10:11]
	v_mov_b64_e32 v[58:59], v[22:23]
	v_mov_b64_e32 v[70:71], v[34:35]
	v_mov_b64_e32 v[54:55], v[18:19]
	v_mov_b64_e32 v[62:63], v[30:31]
	v_mov_b64_e32 v[74:75], v[38:39]
	v_cmp_lt_u32_e64 s[40:41], 63, v123
	v_xor_b32_e32 v130, 63, v126
	v_xor_b32_e32 v131, 63, v128
	v_xor_b32_e32 v132, 63, v129
	v_xor_b32_e32 v133, 63, v123
	v_add3_u32 v165, v124, v2, v113
	v_add_u32_e32 v167, s2, v95
	v_lshlrev_b32_e32 v108, 1, v100
	v_lshlrev_b32_e32 v110, 1, v102
	v_lshlrev_b32_e32 v112, 1, v104
	v_lshlrev_b32_e32 v114, 1, v0
	v_mov_b32_e32 v109, v101
	v_mov_b64_e32 v[40:41], v[4:5]
	v_mov_b64_e32 v[48:49], v[12:13]
	v_mov_b64_e32 v[64:65], v[24:25]
	v_mov_b64_e32 v[44:45], v[8:9]
	v_mov_b64_e32 v[56:57], v[20:21]
	v_mov_b64_e32 v[68:69], v[32:33]
	v_mov_b64_e32 v[52:53], v[16:17]
	v_mov_b64_e32 v[60:61], v[28:29]
	v_mov_b64_e32 v[72:73], v[36:37]
	v_mov_b32_e32 v111, v103
	v_mov_b32_e32 v168, v105
	v_mov_b32_e32 v113, v117
	s_branch .LBB0_620

.LBB0_620:
	s_cmp_eq_u32 s101, 0x5a5a
	s_cbranch_scc1 .Lmlb_have
	v_lshl_add_u32 v238, s1, 1, v122
	v_and_b32_e32 v238, 3, v238
	v_readlane_b32 s100, v255, 7
	s_nop 3
	v_or_b32_e32 v238, s100, v238
	v_ashrrev_i32_e32 v239, 31, v238
	v_lshlrev_b64 v[238:239], 2, v[238:239]
	s_waitcnt lgkmcnt(0)
	v_lshl_add_u64 v[240:241], s[90:91], 0, v[238:239]
	global_load_dword v234, v[240:241], off
	global_load_dword v235, v[240:241], off offset:16
	v_lshl_add_u64 v[242:243], s[88:89], 0, v[238:239]
	global_load_dword v236, v[242:243], off
	global_load_dword v237, v[242:243], off offset:16
	s_waitcnt vmcnt(0)
	s_mov_b32 s101, 0x5a5a

.LBB0_630:
	v_cndmask_b32_e64 v0, v130, v126, s[70:71]
	s_movk_i32 s1, 0x68
	v_mad_u32_u24 v0, v0, s1, v100
	v_lshl_add_u32 v0, v0, 1, v124
	s_waitcnt lgkmcnt(0)
	s_barrier
	ds_write_b128 v0, v[4:7]
	ds_write_b128 v0, v[8:11] offset:13312
	ds_write_b128 v0, v[16:19] offset:26624
	v_cndmask_b32_e64 v0, v131, v128, s[70:71]
	v_mad_u32_u24 v0, v0, s1, v102
	v_lshl_add_u32 v0, v0, 1, v124
	ds_write_b128 v0, v[12:15]
	ds_write_b128 v0, v[20:23] offset:13312
	ds_write_b128 v0, v[28:31] offset:26624
	v_cndmask_b32_e64 v0, v132, v129, s[70:71]
	v_mad_u32_u24 v0, v0, s1, v104
	v_lshl_add_u32 v0, v0, 1, v124
	ds_write_b128 v0, v[24:27]
	ds_write_b128 v0, v[32:35] offset:13312
	ds_write_b128 v0, v[36:39] offset:26624
	s_and_saveexec_b64 s[96:97], s[42:43]
	s_cbranch_execz .LBB0_633
	s_lshl_b32 s1, s76, 2
	s_cmp_eq_u32 s76, 0
	s_cselect_b64 vcc, -1, 0
	s_nop 0
	v_cndmask_b32_e32 v0, v235, v234, vcc
	v_cndmask_b32_e32 v2, v237, v236, vcc
	v_cndmask_b32_e64 v78, v101, v117, s[70:71]
	v_lshlrev_b32_e32 v78, 16, v78
	s_mov_b64 vcc, s[70:71]
	v_and_b32_e32 v79, 64, v209
	v_add_u32_e32 v80, -1, v209
	v_add_u32_e32 v81, -2, v209
	v_cndmask_b32_sdwa v76, v105, v103, vcc dst_sel:WORD_1 dst_unused:UNUSED_PAD src0_sel:DWORD src1_sel:DWORD
	v_cmp_lt_i32_e32 vcc, v80, v79
	v_add_u32_e32 v82, -4, v209
	v_add_u32_e32 v83, -8, v209
	v_cndmask_b32_e32 v80, v80, v209, vcc
	v_cmp_lt_i32_e32 vcc, v81, v79
	v_add_u32_e32 v84, -16, v209
	v_subrev_u32_e32 v85, 32, v209
	v_cndmask_b32_e32 v81, v81, v209, vcc
	v_cmp_lt_i32_e32 vcc, v82, v79
	v_cndmask_b32_e64 v77, v133, v123, s[70:71]
	v_xor_b32_e32 v87, 32, v209
	v_cndmask_b32_e32 v82, v82, v209, vcc
	v_xor_b32_e32 v88, 16, v209
	v_xor_b32_e32 v89, 8, v209
	v_xor_b32_e32 v90, 4, v209
	v_xor_b32_e32 v3, 2, v209
	v_lshl_or_b32 v86, v209, 2, v224
	v_xor_b32_e32 v91, 1, v209
	s_lshl_b64 s[38:39], s[76:77], 2
	s_nop 0
	v_add_f32_e32 v0, v0, v78
	v_mul_f32_e64 v78, |v0|, s36
	v_exp_f32_e32 v78, v78
	v_min_f32_e32 v0, 0, v0
	v_add_f32_e32 v78, 1.0, v78
	v_cmp_gt_f32_e32 vcc, s5, v78
	s_nop 1
	v_cndmask_b32_e64 v92, 0, 32, vcc
	v_ldexp_f32 v78, v78, v92
	v_log_f32_e32 v78, v78
	v_lshlrev_b32_e32 v92, 2, v80
	v_cndmask_b32_e32 v80, 0, v223, vcc
	v_mul_f32_e32 v93, 0x3f317217, v78
	v_fma_f32 v93, v78, s75, -v93
	v_fmac_f32_e32 v93, 0x3377d1cf, v78
	v_fmac_f32_e32 v93, 0x3f317217, v78
	v_cmp_lt_f32_e64 vcc, |v78|, s33
	s_nop 1
	v_cndmask_b32_e32 v78, v78, v93, vcc
	v_sub_f32_e32 v78, v78, v80
	v_sub_f32_e32 v0, v0, v78
	ds_bpermute_b32 v78, v92, v0
	v_lshlrev_b32_e32 v93, 2, v81
	v_cmp_lt_i32_e32 vcc, v83, v79
	v_or_b32_e32 v80, v77, v171
	s_waitcnt lgkmcnt(0)
	v_add_f32_e32 v78, v0, v78
	v_cndmask_b32_e64 v0, v78, v0, s[44:45]
	ds_bpermute_b32 v78, v93, v0
	v_cndmask_b32_e32 v83, v83, v209, vcc
	v_cmp_lt_i32_e32 vcc, v84, v79
	v_lshlrev_b32_e32 v94, 2, v83
	s_waitcnt lgkmcnt(0)
	v_add_f32_e32 v78, v0, v78
	v_cndmask_b32_e32 v84, v84, v209, vcc
	v_cmp_lt_i32_e32 vcc, v85, v79
	v_cndmask_b32_e64 v0, v78, v0, s[46:47]
	v_lshlrev_b32_e32 v95, 2, v84
	v_cndmask_b32_e32 v81, v85, v209, vcc
	v_lshlrev_b32_e32 v85, 2, v82
	ds_bpermute_b32 v78, v85, v0
	v_add_u32_e32 v79, 64, v79
	v_lshlrev_b32_e32 v96, 2, v81
	v_cmp_lt_i32_e32 vcc, v87, v79
	v_ashrrev_i32_e32 v81, 31, v80
	s_waitcnt lgkmcnt(0)
	v_add_f32_e32 v77, v0, v78
	v_cndmask_b32_e64 v0, v77, v0, s[48:49]
	ds_bpermute_b32 v77, v94, v0
	v_cndmask_b32_e32 v78, v209, v87, vcc
	v_cmp_lt_i32_e32 vcc, v88, v79
	v_lshlrev_b64 v[80:81], 3, v[80:81]
	v_or3_b32 v81, v81, s39, 0
	s_waitcnt lgkmcnt(0)
	v_add_f32_e32 v77, v0, v77
	v_cndmask_b32_e64 v0, v77, v0, s[50:51]
	ds_bpermute_b32 v77, v95, v0
	v_cndmask_b32_e32 v82, v209, v88, vcc
	v_cmp_lt_i32_e32 vcc, v89, v79
	v_or3_b32 v80, v80, s38, v116
	s_waitcnt lgkmcnt(0)
	v_add_f32_e32 v77, v0, v77
	v_cndmask_b32_e64 v0, v77, v0, s[52:53]
	ds_bpermute_b32 v77, v96, v0
	v_cndmask_b32_e32 v83, v209, v89, vcc
	v_cmp_lt_i32_e32 vcc, v90, v79
	v_lshlrev_b32_e32 v89, 2, v82
	s_nop 0
	v_cndmask_b32_e32 v84, v209, v90, vcc
	v_cmp_lt_i32_e32 vcc, v3, v79
	v_lshlrev_b32_e32 v90, 2, v83
	s_nop 0
	v_cndmask_b32_e32 v87, v209, v3, vcc
	s_waitcnt lgkmcnt(0)
	v_add_f32_e32 v3, v0, v77
	v_cndmask_b32_e64 v3, v3, v0, s[54:55]
	ds_bpermute_b32 v77, v86, v3
	v_cmp_lt_i32_e32 vcc, v91, v79
	v_lshlrev_b32_e32 v86, 2, v78
	s_waitcnt lgkmcnt(0)
	v_pk_add_f32 v[78:79], v[2:3], v[76:77]
	v_sub_f32_e32 v0, v77, v3
	v_pk_add_f32 v[82:83], v[78:79], v[0:1] op_sel_hi:[1,0]
	v_sub_f32_e32 v79, v78, v3
	ds_bpermute_b32 v0, v86, v82
	ds_bpermute_b32 v2, v92, v79
	v_cndmask_b32_e32 v88, v209, v91, vcc
	v_lshlrev_b32_e32 v91, 2, v84
	v_lshlrev_b32_e32 v76, 2, v87
	s_waitcnt lgkmcnt(1)
	v_max_f32_e32 v0, v0, v0
	s_waitcnt lgkmcnt(0)
	v_max_f32_e32 v2, v2, v2
	v_max_f32_e32 v0, v82, v0
	v_max_f32_e32 v2, v79, v2
	ds_bpermute_b32 v78, v89, v0
	v_cndmask_b32_e64 v2, v2, v79, s[44:45]
	ds_bpermute_b32 v84, v93, v2
	v_lshlrev_b32_e32 v83, 2, v88
	s_waitcnt lgkmcnt(1)
	v_max_f32_e32 v78, v78, v78
	v_max_f32_e32 v0, v0, v78
	s_waitcnt lgkmcnt(0)
	v_max_f32_e32 v78, v84, v84
	v_max_f32_e32 v78, v2, v78
	ds_bpermute_b32 v86, v90, v0
	v_cndmask_b32_e64 v2, v78, v2, s[46:47]
	ds_bpermute_b32 v78, v85, v2
	v_lshl_add_u64 v[84:85], v[80:81], 4, s[12:13]
	s_waitcnt lgkmcnt(1)
	v_max_f32_e32 v80, v86, v86
	v_max_f32_e32 v0, v0, v80
	s_waitcnt lgkmcnt(0)
	v_max_f32_e32 v78, v78, v78
	ds_bpermute_b32 v80, v91, v0
	v_max_f32_e32 v78, v2, v78
	v_cndmask_b32_e64 v2, v78, v2, s[48:49]
	ds_bpermute_b32 v81, v94, v2
	v_mov_b32_e32 v78, v3
	s_waitcnt lgkmcnt(1)
	v_max_f32_e32 v3, v80, v80
	v_max_f32_e32 v0, v0, v3
	ds_bpermute_b32 v3, v76, v0
	s_waitcnt lgkmcnt(1)
	v_max_f32_e32 v76, v81, v81
	v_max_f32_e32 v76, v2, v76
	v_cndmask_b32_e64 v2, v76, v2, s[50:51]
	ds_bpermute_b32 v76, v95, v2
	s_waitcnt lgkmcnt(1)
	v_max_f32_e32 v3, v3, v3
	v_max_f32_e32 v0, v0, v3
	ds_bpermute_b32 v3, v83, v0
	v_mov_b32_e32 v81, v82
	s_waitcnt lgkmcnt(1)
	v_max_f32_e32 v76, v76, v76
	v_max_f32_e32 v76, v2, v76
	v_cndmask_b32_e64 v2, v76, v2, s[52:53]
	ds_bpermute_b32 v76, v96, v2
	s_waitcnt lgkmcnt(1)
	v_max_f32_e32 v3, v3, v3
	v_max_f32_e32 v3, v0, v3
	v_sub_f32_e32 v0, v82, v3
	v_mul_f32_e32 v0, 0x3fb8aa3b, v0
	v_max_f32_e32 v80, v2, v2
	v_exp_f32_e32 v0, v0
	s_waitcnt lgkmcnt(0)
	v_max_f32_e32 v76, v76, v76
	v_max_f32_e32 v76, v80, v76
	v_cndmask_b32_e64 v80, v76, v2, s[54:55]
	global_store_dwordx4 v[84:85], v[78:81], off
	ds_write2st64_b32 v134, v79, v80 offset0:192 offset1:193
	ds_write_b32 v134, v0 offset:49664
	s_and_b64 exec, exec, s[44:45]
	s_cbranch_execz .LBB0_633
	v_or_b32_e32 v0, s1, v172
	v_lshlrev_b32_e32 v78, 1, v0
	v_ashrrev_i32_e32 v79, 31, v78
	v_lshl_add_u64 v[78:79], v[78:79], 2, s[22:23]
	v_mov_b32_e32 v2, v77
	global_store_dwordx2 v[78:79], v[2:3], off
